# prologue x-loop restored to the original form (probe showed the batched-load version slower); keeps early-invalidate barrier, RSTD pre-pass batch, pool through LDS
# baseline (speedup 1.0000x reference)
; __device__ __forceinline__ size_t oq(size_t c) { asm volatile("" : "+s"(c)); return c; }
; #define PHASE_IDS() const int tid = opaque_tid(), lane = tid & 63, wave = __builtin_amdgcn_readfirstlane(tid >> 6); (void)lane; (void)wave
; __device__ __forceinline__ void p_pool(Frame& F) {
;     PHASE_IDS();
;     const bf16_t* ZP = (const bf16_t*)(F.ws + oq(WS_ZP)); bf16_t* PO = (bf16_t*)(F.ws + oq(WS_POOLED));
;     for (int id = F.vcu * 512 + tid; id < (MROWS / 8) * 128; id += F.G * 512) {
;         const int cg = id & 127, run = id >> 7, r0 = run * 8, t0 = r0 & (SEQ - 1), w = 2 << (cg >> 5);
;         f32x4 s0 = {0.f, 0.f, 0.f, 0.f}, s1 = {0.f, 0.f, 0.f, 0.f};
;         for (int j = 1; j < w; ++j) if (t0 - j >= 0) { f32x4 a, b; ld_bf16x8(ZP + (size_t)(r0 - j) * PD + 8 * cg, a, b); s0 += a; s1 += b; }
; #pragma unroll
;         for (int i = 0; i < 8; ++i) { const int t = t0 + i; f32x4 a, b; ld_bf16x8(ZP + (size_t)(r0 + i) * PD + 8 * cg, a, b); s0 += a; s1 += b;
.LBB0_588:
	s_andn2_b64 vcc, exec, s[0:1]
	s_cbranch_vccnz .LBB0_674
	v_mov_b32_e32 v2, v0
	v_readlane_b32 s0, v245, 57
	s_mov_b64 s[4:5], 0x28000000
	s_mov_b64 s[6:7], 0x33000000
	s_waitcnt vmcnt(0)
	v_add_u32_e32 v26, s0, v2
	s_lshr_b32 s14, s0, 4
	s_and_b32 s16, s14, 0x7ff
	s_lshl_b32 s14, s14, 11
	s_add_u32 s14, s14, 0x27ff8800
	s_add_u32 s98, s54, s14
	s_addc_u32 s99, s55, 0
	v_lshrrev_b32_e32 v4, 6, v2
	v_and_b32_e32 v5, 63, v2
	v_readfirstlane_b32 s15, v4
	v_lshlrev_b32_e32 v5, 4, v5
	v_lshl_add_u32 v5, v4, 10, v5
	s_nop 3
	s_lshl_b32 s15, s15, 10
	s_mov_b32 s14, m0
	s_cmp_lg_u32 s16, 0
	s_cbranch_scc1 .Lpool_full
	v_add_u32_e32 v5, 0x6000, v5
	s_cmp_ge_u32 s15, 0x1800
	s_cbranch_scc1 .Lpool_q3
	v_add_u32_e32 v5, 0x2000, v5
	s_branch .Lpool_q4
.Lpool_full:
	s_add_i32 m0, s15, 0x0
	s_nop 0
	global_load_lds_dwordx4 v5, s[98:99]
	v_add_u32_e32 v5, 0x2000, v5
	s_add_i32 m0, s15, 0x2000
	s_nop 0
	global_load_lds_dwordx4 v5, s[98:99]
	v_add_u32_e32 v5, 0x2000, v5
	s_add_i32 m0, s15, 0x4000
	s_nop 0
	global_load_lds_dwordx4 v5, s[98:99]
	v_add_u32_e32 v5, 0x2000, v5
.Lpool_q3:
	s_add_i32 m0, s15, 0x6000
	s_nop 0
	global_load_lds_dwordx4 v5, s[98:99]
	v_add_u32_e32 v5, 0x2000, v5
.Lpool_q4:
	s_add_i32 m0, s15, 0x8000
	s_nop 0
	global_load_lds_dwordx4 v5, s[98:99]
	v_add_u32_e32 v5, 0x2000, v5
	s_add_i32 m0, s15, 0xa000
	s_nop 0
	global_load_lds_dwordx4 v5, s[98:99]
	v_add_u32_e32 v5, 0x2000, v5
	s_add_i32 m0, s15, 0xc000
	s_nop 0
	global_load_lds_dwordx4 v5, s[98:99]
	v_add_u32_e32 v5, 0x2000, v5
	s_add_i32 m0, s15, 0xe000
	s_nop 0
	global_load_lds_dwordx4 v5, s[98:99]
	v_add_u32_e32 v5, 0x2000, v5
	s_add_i32 m0, s15, 0x10000
	s_nop 0
	global_load_lds_dwordx4 v5, s[98:99]
	v_add_u32_e32 v5, 0x2000, v5
	s_add_i32 m0, s15, 0x12000
	s_nop 0
	global_load_lds_dwordx4 v5, s[98:99]
	v_add_u32_e32 v5, 0x2000, v5
	s_add_i32 m0, s15, 0x14000
	s_nop 0
	global_load_lds_dwordx4 v5, s[98:99]
	v_add_u32_e32 v5, 0x2000, v5
	s_cmp_lt_u32 s15, 0x1800
	s_cbranch_scc0 .Lpool_staged
	s_add_i32 m0, s15, 0x16000
	s_nop 0
	global_load_lds_dwordx4 v5, s[98:99]
	v_add_u32_e32 v5, 0x2000, v5

; __device__ __forceinline__ void p_pool(Frame& F) {
;     ...
;         for (int i = 0; i < 8; ++i) { const int t = t0 + i; f32x4 a, b; ld_bf16x8(ZP + (size_t)(r0 + i) * PD + 8 * cg, a, b); s0 += a; s1 += b;
;             const float inv = 1.0f / (float)((t + 1) < w ? (t + 1) : w);
;             st_bf16x8(PO + (size_t)(r0 + i) * PD + 8 * cg, s0 * inv - a, s1 * inv - b);
;             if (t - w + 1 >= 0) { f32x4 c, d; ld_bf16x8(ZP + (size_t)(r0 + i - w + 1) * PD + 8 * cg, c, d); s0 -= c; s1 -= d; } }
;     }
.LBB0_591:
	s_or_b64 exec, exec, s[6:7]
	v_or_b32_e32 v12, 7, v30
	v_ashrrev_i32_e32 v13, 31, v12
	v_lshlrev_b64 v[12:13], 11, v[12:13]
	v_lshl_add_u64 v[20:21], v[14:15], 0, v[12:13]
	v_subrev_u32_e32 v20, s98, v20
	ds_read_b128 v[20:23], v20
	v_add_u32_e32 v2, 8, v29
	v_min_u32_e32 v2, v2, v27
	v_cvt_f32_ubyte0_e32 v2, v2
	v_div_scale_f32 v29, s[6:7], v2, v2, 1.0
	v_rcp_f32_e32 v32, v29
	v_add_u32_e32 v26, s17, v26
	s_mov_b32 s6, 0x1ffff
	v_lshl_add_u64 v[12:13], v[16:17], 0, v[12:13]
	v_fma_f32 v33, -v29, v32, 1.0
	v_fmac_f32_e32 v32, v33, v32
	v_div_scale_f32 v33, vcc, 1.0, v2, 1.0
	v_mul_f32_e32 v34, v33, v32
	v_fma_f32 v35, -v29, v34, v33
	v_fmac_f32_e32 v34, v35, v32
	v_fma_f32 v29, -v29, v34, v33
	v_div_fmas_f32 v29, v29, v32, v34
	v_div_fixup_f32 v2, v29, v2, 1.0
	v_cmp_lt_i32_e32 vcc, s6, v26
	s_or_b64 s[4:5], vcc, s[4:5]
	s_waitcnt lgkmcnt(0)
	v_lshlrev_b32_e32 v24, 16, v20
	v_and_b32_e32 v25, 0xffff0000, v20
	v_lshlrev_b32_e32 v20, 16, v21
	v_and_b32_e32 v21, 0xffff0000, v21
	v_pk_add_f32 v[4:5], v[4:5], v[20:21]
	v_xor_b32_e32 v21, 0x80000000, v21
	v_xor_b32_e32 v20, 0x80000000, v20
	v_lshlrev_b32_e32 v30, 16, v22
	v_and_b32_e32 v31, 0xffff0000, v22
	v_lshlrev_b32_e32 v22, 16, v23
	v_and_b32_e32 v23, 0xffff0000, v23
	v_pk_add_f32 v[8:9], v[8:9], v[24:25]
	v_pk_fma_f32 v[20:21], v[2:3], v[4:5], v[20:21] op_sel_hi:[0,1,1]
	v_xor_b32_e32 v5, 0x80000000, v25
	v_xor_b32_e32 v4, 0x80000000, v24
	v_pk_add_f32 v[6:7], v[6:7], v[22:23]
	v_pk_fma_f32 v[4:5], v[2:3], v[8:9], v[4:5] op_sel_hi:[0,1,1]
	v_xor_b32_e32 v9, 0x80000000, v23
	v_xor_b32_e32 v8, 0x80000000, v22
	v_pk_add_f32 v[10:11], v[10:11], v[30:31]
	v_pk_fma_f32 v[8:9], v[2:3], v[6:7], v[8:9] op_sel_hi:[0,1,1]
	v_xor_b32_e32 v7, 0x80000000, v31
	v_xor_b32_e32 v6, 0x80000000, v30
	v_pk_fma_f32 v[6:7], v[2:3], v[10:11], v[6:7] op_sel_hi:[0,1,1]
	v_cvt_pk_bf16_f32 v4, v4, v5
	v_cvt_pk_bf16_f32 v5, v20, v21
	v_cvt_pk_bf16_f32 v6, v6, v7
	v_cvt_pk_bf16_f32 v7, v8, v9
	global_store_dwordx4 v[12:13], v[4:7], off
	s_andn2_b64 exec, exec, s[4:5]
	s_cbranch_execz .LBB0_610

; __device__ __forceinline__ void p_pool(Frame& F) {
;     ...
;         for (int j = 1; j < w; ++j) if (t0 - j >= 0) { f32x4 a, b; ld_bf16x8(ZP + (size_t)(r0 - j) * PD + 8 * cg, a, b); s0 += a; s1 += b; }
; #pragma unroll
;         for (int i = 0; i < 8; ++i) { const int t = t0 + i; f32x4 a, b; ld_bf16x8(ZP + (size_t)(r0 + i) * PD + 8 * cg, a, b); s0 += a; s1 += b;
;             const float inv = 1.0f / (float)((t + 1) < w ? (t + 1) : w);
;             st_bf16x8(PO + (size_t)(r0 + i) * PD + 8 * cg, s0 * inv - a, s1 * inv - b);
;             if (t - w + 1 >= 0) { f32x4 c, d; ld_bf16x8(ZP + (size_t)(r0 + i - w + 1) * PD + 8 * cg, c, d); s0 -= c; s1 -= d; } }
.LBB0_594:
	v_cmp_le_u32_e32 vcc, s16, v29
	s_and_saveexec_b64 s[14:15], vcc
	s_cbranch_execz .LBB0_593
	v_subrev_u32_e32 v32, s98, v22
	ds_read_b128 v[32:35], v32
	s_waitcnt lgkmcnt(0)
	v_lshlrev_b32_e32 v4, 16, v32
	v_and_b32_e32 v5, 0xffff0000, v32
	v_lshlrev_b32_e32 v32, 16, v33
	v_and_b32_e32 v33, 0xffff0000, v33
	v_lshlrev_b32_e32 v36, 16, v34
	v_and_b32_e32 v37, 0xffff0000, v34
	v_lshlrev_b32_e32 v34, 16, v35
	v_and_b32_e32 v35, 0xffff0000, v35
	v_pk_add_f32 v[12:13], v[12:13], v[32:33]
	v_pk_add_f32 v[10:11], v[10:11], v[4:5]
	v_pk_add_f32 v[8:9], v[8:9], v[34:35]
	v_pk_add_f32 v[6:7], v[6:7], v[36:37]
	s_branch .LBB0_593
.LBB0_596:
	s_or_b64 exec, exec, s[6:7]
	v_lshl_add_u64 v[4:5], v[14:15], 0, v[24:25]
	v_subrev_u32_e32 v32, s98, v4
	ds_read_b128 v[32:35], v32
	v_or_b32_e32 v2, 1, v29
	v_min_u32_e32 v2, v2, v27
	v_cvt_f32_ubyte0_e32 v2, v2
	s_waitcnt lgkmcnt(0)
	v_lshlrev_b32_e32 v36, 16, v32
	v_and_b32_e32 v37, 0xffff0000, v32
	v_pk_add_f32 v[4:5], v[10:11], v[36:37]
	v_div_scale_f32 v10, s[6:7], v2, v2, 1.0
	v_rcp_f32_e32 v11, v10
	v_lshlrev_b32_e32 v32, 16, v33
	v_and_b32_e32 v33, 0xffff0000, v33
	v_lshlrev_b32_e32 v22, 16, v34
	v_fma_f32 v21, -v10, v11, 1.0
	v_fmac_f32_e32 v11, v21, v11
	v_div_scale_f32 v21, vcc, 1.0, v2, 1.0
	v_mul_f32_e32 v31, v21, v11
	v_fma_f32 v38, -v10, v31, v21
	v_fmac_f32_e32 v31, v38, v11
	v_fma_f32 v10, -v10, v31, v21
	v_and_b32_e32 v23, 0xffff0000, v34
	v_lshlrev_b32_e32 v34, 16, v35
	v_and_b32_e32 v35, 0xffff0000, v35
	v_div_fmas_f32 v10, v10, v11, v31
	v_pk_add_f32 v[12:13], v[12:13], v[32:33]
	v_pk_add_f32 v[8:9], v[8:9], v[34:35]
	v_pk_add_f32 v[6:7], v[6:7], v[22:23]
	v_div_fixup_f32 v2, v10, v2, 1.0
	v_lshl_add_u64 v[10:11], v[16:17], 0, v[24:25]
	v_xor_b32_e32 v25, 0x80000000, v33
	v_xor_b32_e32 v24, 0x80000000, v32
	v_xor_b32_e32 v33, 0x80000000, v37
	v_xor_b32_e32 v32, 0x80000000, v36
	v_xor_b32_e32 v35, 0x80000000, v35
	v_xor_b32_e32 v34, 0x80000000, v34
	v_xor_b32_e32 v23, 0x80000000, v23
	v_xor_b32_e32 v22, 0x80000000, v22
	v_pk_fma_f32 v[24:25], v[2:3], v[12:13], v[24:25] op_sel_hi:[0,1,1]
	v_pk_fma_f32 v[32:33], v[2:3], v[4:5], v[32:33] op_sel_hi:[0,1,1]
	v_pk_fma_f32 v[34:35], v[2:3], v[8:9], v[34:35] op_sel_hi:[0,1,1]
	v_pk_fma_f32 v[36:37], v[2:3], v[6:7], v[22:23] op_sel_hi:[0,1,1]
	v_cvt_pk_bf16_f32 v22, v32, v33
	v_cvt_pk_bf16_f32 v23, v24, v25
	v_cvt_pk_bf16_f32 v24, v36, v37
	v_cvt_pk_bf16_f32 v25, v34, v35
	v_cmp_ge_u32_e32 vcc, v29, v27
	global_store_dwordx4 v[10:11], v[22:25], off
	s_and_saveexec_b64 s[6:7], vcc
	s_cbranch_execz .LBB0_598
	v_sub_u32_e32 v2, v20, v27
	v_or_b32_e32 v10, 1, v2
	v_ashrrev_i32_e32 v11, 31, v10
	v_lshlrev_b64 v[10:11], 11, v[10:11]
	v_lshl_add_u64 v[10:11], v[14:15], 0, v[10:11]
	v_subrev_u32_e32 v22, s98, v10
	ds_read_b128 v[22:25], v22
	s_waitcnt lgkmcnt(0)
	v_lshlrev_b32_e32 v2, 16, v22
	v_and_b32_e32 v10, 0xffff0000, v22
	v_lshlrev_b32_e32 v11, 16, v23
	v_and_b32_e32 v21, 0xffff0000, v23
	v_lshlrev_b32_e32 v22, 16, v24
	v_and_b32_e32 v23, 0xffff0000, v24
	v_lshlrev_b32_e32 v24, 16, v25
	v_and_b32_e32 v25, 0xffff0000, v25
	v_sub_f32_e32 v13, v13, v21
	v_sub_f32_e32 v12, v12, v11
	v_sub_f32_e32 v5, v5, v10
	v_sub_f32_e32 v4, v4, v2
	v_sub_f32_e32 v9, v9, v25
	v_sub_f32_e32 v8, v8, v24
	v_sub_f32_e32 v7, v7, v23
	v_sub_f32_e32 v6, v6, v22
.LBB0_598:
	s_or_b64 exec, exec, s[6:7]
	v_or_b32_e32 v22, 1, v20
	v_ashrrev_i32_e32 v23, 31, v22
	v_lshlrev_b64 v[24:25], 11, v[22:23]
	v_lshl_add_u64 v[10:11], v[14:15], 0, v[24:25]
	v_subrev_u32_e32 v32, s98, v10
	ds_read_b128 v[32:35], v32
	v_or_b32_e32 v2, 2, v29
	v_min_u32_e32 v2, v2, v27
	v_cvt_f32_ubyte0_e32 v2, v2
	v_cmp_ge_i32_e64 s[40:41], v29, v28
	s_waitcnt lgkmcnt(0)
	v_lshlrev_b32_e32 v36, 16, v32
	v_and_b32_e32 v37, 0xffff0000, v32
	v_lshlrev_b32_e32 v32, 16, v33
	v_and_b32_e32 v33, 0xffff0000, v33
	v_lshlrev_b32_e32 v38, 16, v34
	v_and_b32_e32 v39, 0xffff0000, v34
	v_lshlrev_b32_e32 v34, 16, v35
	v_and_b32_e32 v35, 0xffff0000, v35
	v_pk_add_f32 v[10:11], v[12:13], v[32:33]
	v_pk_add_f32 v[12:13], v[4:5], v[36:37]
	v_pk_add_f32 v[4:5], v[8:9], v[34:35]
	v_pk_add_f32 v[8:9], v[6:7], v[38:39]
	v_div_scale_f32 v6, s[6:7], v2, v2, 1.0
	v_rcp_f32_e32 v7, v6
	v_xor_b32_e32 v35, 0x80000000, v35
	v_xor_b32_e32 v34, 0x80000000, v34
	v_fma_f32 v21, -v6, v7, 1.0
	v_fmac_f32_e32 v7, v21, v7
	v_div_scale_f32 v21, vcc, 1.0, v2, 1.0
	v_mul_f32_e32 v23, v21, v7
	v_fma_f32 v31, -v6, v23, v21
	v_fmac_f32_e32 v23, v31, v7
	v_fma_f32 v6, -v6, v23, v21
	v_div_fmas_f32 v6, v6, v7, v23
	v_div_fixup_f32 v2, v6, v2, 1.0
	v_lshl_add_u64 v[6:7], v[16:17], 0, v[24:25]
	v_xor_b32_e32 v25, 0x80000000, v33
	v_xor_b32_e32 v24, 0x80000000, v32
	v_xor_b32_e32 v33, 0x80000000, v37
	v_xor_b32_e32 v32, 0x80000000, v36
	v_pk_fma_f32 v[36:37], v[2:3], v[4:5], v[34:35] op_sel_hi:[0,1,1]
	v_xor_b32_e32 v35, 0x80000000, v39
	v_xor_b32_e32 v34, 0x80000000, v38
	v_pk_fma_f32 v[24:25], v[2:3], v[10:11], v[24:25] op_sel_hi:[0,1,1]
	v_pk_fma_f32 v[32:33], v[2:3], v[12:13], v[32:33] op_sel_hi:[0,1,1]
	v_pk_fma_f32 v[34:35], v[2:3], v[8:9], v[34:35] op_sel_hi:[0,1,1]
	v_cvt_pk_bf16_f32 v32, v32, v33
	v_cvt_pk_bf16_f32 v33, v24, v25
	v_cvt_pk_bf16_f32 v34, v34, v35
	v_cvt_pk_bf16_f32 v35, v36, v37
	global_store_dwordx4 v[6:7], v[32:35], off
	s_and_saveexec_b64 s[6:7], s[40:41]
	s_cbranch_execz .LBB0_600
	v_sub_u32_e32 v6, v22, v27
	v_ashrrev_i32_e32 v7, 31, v6
	v_lshlrev_b64 v[6:7], 11, v[6:7]
	v_lshl_add_u64 v[6:7], v[14:15], 0, v[6:7]
	v_subrev_u32_e32 v22, s98, v6
	ds_read_b128 v[22:25], v22 offset:2048
	s_waitcnt lgkmcnt(0)
	v_lshlrev_b32_e32 v2, 16, v22
	v_and_b32_e32 v6, 0xffff0000, v22
	v_lshlrev_b32_e32 v7, 16, v23
	v_and_b32_e32 v21, 0xffff0000, v23
	v_lshlrev_b32_e32 v22, 16, v24
	v_and_b32_e32 v23, 0xffff0000, v24
	v_lshlrev_b32_e32 v24, 16, v25
	v_and_b32_e32 v25, 0xffff0000, v25
	v_sub_f32_e32 v11, v11, v21
	v_sub_f32_e32 v10, v10, v7
	v_sub_f32_e32 v13, v13, v6
	v_sub_f32_e32 v12, v12, v2
	v_sub_f32_e32 v5, v5, v25
	v_sub_f32_e32 v4, v4, v24
	v_sub_f32_e32 v9, v9, v23
	v_sub_f32_e32 v8, v8, v22
; __device__ __forceinline__ void p_pool(Frame& F) {
;     ...
;         for (int i = 0; i < 8; ++i) { const int t = t0 + i; f32x4 a, b; ld_bf16x8(ZP + (size_t)(r0 + i) * PD + 8 * cg, a, b); s0 += a; s1 += b;
;             const float inv = 1.0f / (float)((t + 1) < w ? (t + 1) : w);
;             st_bf16x8(PO + (size_t)(r0 + i) * PD + 8 * cg, s0 * inv - a, s1 * inv - b);
;             if (t - w + 1 >= 0) { f32x4 c, d; ld_bf16x8(ZP + (size_t)(r0 + i - w + 1) * PD + 8 * cg, c, d); s0 -= c; s1 -= d; } }
.LBB0_600:
	s_or_b64 exec, exec, s[6:7]
	v_or_b32_e32 v22, 2, v20
	v_ashrrev_i32_e32 v23, 31, v22
	v_lshlrev_b64 v[24:25], 11, v[22:23]
	v_lshl_add_u64 v[6:7], v[14:15], 0, v[24:25]
	v_subrev_u32_e32 v32, s98, v6
	ds_read_b128 v[32:35], v32
	v_or_b32_e32 v2, 3, v29
	v_lshl_add_u64 v[24:25], v[16:17], 0, v[24:25]
	s_waitcnt lgkmcnt(0)
	v_lshlrev_b32_e32 v36, 16, v32
	v_and_b32_e32 v37, 0xffff0000, v32
	v_lshlrev_b32_e32 v32, 16, v33
	v_and_b32_e32 v33, 0xffff0000, v33
	v_pk_add_f32 v[6:7], v[10:11], v[32:33]
	v_pk_add_f32 v[10:11], v[12:13], v[36:37]
	v_min_u32_e32 v12, v2, v27
	v_cvt_f32_ubyte0_e32 v12, v12
	v_div_scale_f32 v13, s[6:7], v12, v12, 1.0
	v_rcp_f32_e32 v21, v13
	v_lshlrev_b32_e32 v38, 16, v34
	v_and_b32_e32 v39, 0xffff0000, v34
	v_lshlrev_b32_e32 v34, 16, v35
	v_fma_f32 v23, -v13, v21, 1.0
	v_fmac_f32_e32 v21, v23, v21
	v_div_scale_f32 v23, vcc, 1.0, v12, 1.0
	v_mul_f32_e32 v31, v23, v21
	v_fma_f32 v40, -v13, v31, v23
	v_fmac_f32_e32 v31, v40, v21
	v_fma_f32 v13, -v13, v31, v23
	v_and_b32_e32 v35, 0xffff0000, v35
	v_div_fmas_f32 v13, v13, v21, v31
	v_pk_add_f32 v[4:5], v[4:5], v[34:35]
	v_div_fixup_f32 v12, v13, v12, 1.0
	v_xor_b32_e32 v33, 0x80000000, v33
	v_xor_b32_e32 v32, 0x80000000, v32
	v_xor_b32_e32 v35, 0x80000000, v35
	v_xor_b32_e32 v34, 0x80000000, v34
	v_pk_add_f32 v[8:9], v[8:9], v[38:39]
	v_pk_fma_f32 v[40:41], v[12:13], v[6:7], v[32:33] op_sel_hi:[0,1,1]
	v_xor_b32_e32 v33, 0x80000000, v37
	v_xor_b32_e32 v32, 0x80000000, v36
	v_pk_fma_f32 v[36:37], v[12:13], v[4:5], v[34:35] op_sel_hi:[0,1,1]
	v_xor_b32_e32 v35, 0x80000000, v39
	v_xor_b32_e32 v34, 0x80000000, v38
	v_pk_fma_f32 v[32:33], v[12:13], v[10:11], v[32:33] op_sel_hi:[0,1,1]
	v_pk_fma_f32 v[12:13], v[12:13], v[8:9], v[34:35] op_sel_hi:[0,1,1]
	v_cvt_pk_bf16_f32 v32, v32, v33
	v_cvt_pk_bf16_f32 v33, v40, v41
	v_cvt_pk_bf16_f32 v34, v12, v13
	v_cvt_pk_bf16_f32 v35, v36, v37
	global_store_dwordx4 v[24:25], v[32:35], off
	s_and_saveexec_b64 s[6:7], s[40:41]
	s_cbranch_execz .LBB0_602
	v_sub_u32_e32 v12, v22, v27
	v_or_b32_e32 v12, 1, v12
	v_ashrrev_i32_e32 v13, 31, v12
	v_lshlrev_b64 v[12:13], 11, v[12:13]
	v_lshl_add_u64 v[12:13], v[14:15], 0, v[12:13]
	v_subrev_u32_e32 v22, s98, v12
	ds_read_b128 v[22:25], v22
	s_waitcnt lgkmcnt(0)
	v_lshlrev_b32_e32 v12, 16, v22
	v_and_b32_e32 v13, 0xffff0000, v22
	v_lshlrev_b32_e32 v21, 16, v23
	v_and_b32_e32 v22, 0xffff0000, v23
	v_lshlrev_b32_e32 v23, 16, v24
	v_and_b32_e32 v24, 0xffff0000, v24
	v_lshlrev_b32_e32 v31, 16, v25
	v_and_b32_e32 v25, 0xffff0000, v25
	v_sub_f32_e32 v7, v7, v22
	v_sub_f32_e32 v6, v6, v21
	v_sub_f32_e32 v11, v11, v13
	v_sub_f32_e32 v10, v10, v12
	v_sub_f32_e32 v5, v5, v25
	v_sub_f32_e32 v4, v4, v31
	v_sub_f32_e32 v9, v9, v24
	v_sub_f32_e32 v8, v8, v23
.LBB0_602:
	s_or_b64 exec, exec, s[6:7]
	v_or_b32_e32 v24, 3, v20
	v_ashrrev_i32_e32 v25, 31, v24
	v_lshlrev_b64 v[36:37], 11, v[24:25]
	v_lshl_add_u64 v[12:13], v[14:15], 0, v[36:37]
	v_subrev_u32_e32 v32, s98, v12
	ds_read_b128 v[32:35], v32
	v_or_b32_e32 v21, 4, v29
	s_waitcnt lgkmcnt(0)
	v_lshlrev_b32_e32 v38, 16, v32
	v_and_b32_e32 v39, 0xffff0000, v32
	v_lshlrev_b32_e32 v40, 16, v34
	v_and_b32_e32 v41, 0xffff0000, v34
	v_lshlrev_b32_e32 v34, 16, v35
	v_and_b32_e32 v35, 0xffff0000, v35
	v_pk_add_f32 v[12:13], v[10:11], v[38:39]
	v_pk_add_f32 v[10:11], v[4:5], v[34:35]
	v_min_u32_e32 v4, v21, v27
	v_cvt_f32_ubyte0_e32 v4, v4
	v_div_scale_f32 v5, s[6:7], v4, v4, 1.0
	v_pk_add_f32 v[22:23], v[8:9], v[40:41]
	v_rcp_f32_e32 v8, v5
	v_lshlrev_b32_e32 v32, 16, v33
	v_and_b32_e32 v33, 0xffff0000, v33
	v_pk_add_f32 v[6:7], v[6:7], v[32:33]
	v_fma_f32 v9, -v5, v8, 1.0
	v_fmac_f32_e32 v8, v9, v8
	v_div_scale_f32 v9, vcc, 1.0, v4, 1.0
	v_mul_f32_e32 v25, v9, v8
	v_fma_f32 v31, -v5, v25, v9
	v_fmac_f32_e32 v25, v31, v8
	v_fma_f32 v5, -v5, v25, v9
	v_div_fmas_f32 v5, v5, v8, v25
	v_div_fixup_f32 v4, v5, v4, 1.0
	v_xor_b32_e32 v33, 0x80000000, v33
	v_xor_b32_e32 v32, 0x80000000, v32
	v_xor_b32_e32 v35, 0x80000000, v35
	v_xor_b32_e32 v34, 0x80000000, v34
	v_lshl_add_u64 v[8:9], v[16:17], 0, v[36:37]
	v_pk_fma_f32 v[36:37], v[4:5], v[6:7], v[32:33] op_sel_hi:[0,1,1]
	v_xor_b32_e32 v33, 0x80000000, v39
	v_xor_b32_e32 v32, 0x80000000, v38
	v_pk_fma_f32 v[38:39], v[4:5], v[10:11], v[34:35] op_sel_hi:[0,1,1]
	v_xor_b32_e32 v35, 0x80000000, v41
	v_xor_b32_e32 v34, 0x80000000, v40
	v_pk_fma_f32 v[32:33], v[4:5], v[12:13], v[32:33] op_sel_hi:[0,1,1]
	v_pk_fma_f32 v[4:5], v[4:5], v[22:23], v[34:35] op_sel_hi:[0,1,1]
	v_cvt_pk_bf16_f32 v32, v32, v33
	v_cvt_pk_bf16_f32 v33, v36, v37
	v_cvt_pk_bf16_f32 v34, v4, v5
	v_cvt_pk_bf16_f32 v35, v38, v39
	v_cmp_gt_i32_e32 vcc, v2, v28
	global_store_dwordx4 v[8:9], v[32:35], off
	s_and_saveexec_b64 s[6:7], vcc
	s_cbranch_execz .LBB0_604
	v_sub_u32_e32 v4, v24, v27
	v_ashrrev_i32_e32 v5, 31, v4
	v_lshlrev_b64 v[4:5], 11, v[4:5]
	v_lshl_add_u64 v[4:5], v[14:15], 0, v[4:5]
	v_subrev_u32_e32 v32, s98, v4
	ds_read_b128 v[32:35], v32 offset:2048
	s_waitcnt lgkmcnt(0)
	v_lshlrev_b32_e32 v2, 16, v32
	v_and_b32_e32 v4, 0xffff0000, v32
	v_lshlrev_b32_e32 v5, 16, v33
	v_and_b32_e32 v8, 0xffff0000, v33
	v_lshlrev_b32_e32 v9, 16, v34
	v_and_b32_e32 v24, 0xffff0000, v34
	v_lshlrev_b32_e32 v25, 16, v35
	v_and_b32_e32 v31, 0xffff0000, v35
	v_sub_f32_e32 v7, v7, v8
	v_sub_f32_e32 v6, v6, v5
	v_sub_f32_e32 v13, v13, v4
	v_sub_f32_e32 v12, v12, v2
	v_sub_f32_e32 v11, v11, v31
	v_sub_f32_e32 v10, v10, v25
	v_sub_f32_e32 v23, v23, v24
	v_sub_f32_e32 v22, v22, v9
; __device__ __forceinline__ void p_pool(Frame& F) {
;     ...
;         for (int i = 0; i < 8; ++i) { const int t = t0 + i; f32x4 a, b; ld_bf16x8(ZP + (size_t)(r0 + i) * PD + 8 * cg, a, b); s0 += a; s1 += b;
;             const float inv = 1.0f / (float)((t + 1) < w ? (t + 1) : w);
;             st_bf16x8(PO + (size_t)(r0 + i) * PD + 8 * cg, s0 * inv - a, s1 * inv - b);
;             if (t - w + 1 >= 0) { f32x4 c, d; ld_bf16x8(ZP + (size_t)(r0 + i - w + 1) * PD + 8 * cg, c, d); s0 -= c; s1 -= d; } }
.LBB0_604:
	s_or_b64 exec, exec, s[6:7]
	v_or_b32_e32 v24, 4, v20
	v_ashrrev_i32_e32 v25, 31, v24
	v_lshlrev_b64 v[36:37], 11, v[24:25]
	v_lshl_add_u64 v[4:5], v[14:15], 0, v[36:37]
	v_subrev_u32_e32 v32, s98, v4
	ds_read_b128 v[32:35], v32
	v_or_b32_e32 v2, 5, v29
	s_waitcnt lgkmcnt(0)
	v_lshlrev_b32_e32 v38, 16, v32
	v_and_b32_e32 v39, 0xffff0000, v32
	v_pk_add_f32 v[8:9], v[12:13], v[38:39]
	v_min_u32_e32 v12, v2, v27
	v_cvt_f32_ubyte0_e32 v12, v12
	v_lshlrev_b32_e32 v32, 16, v33
	v_and_b32_e32 v33, 0xffff0000, v33
	v_lshlrev_b32_e32 v40, 16, v34
	v_and_b32_e32 v41, 0xffff0000, v34
	v_lshlrev_b32_e32 v34, 16, v35
	v_and_b32_e32 v35, 0xffff0000, v35
	v_div_scale_f32 v13, s[6:7], v12, v12, 1.0
	v_pk_add_f32 v[4:5], v[6:7], v[32:33]
	v_pk_add_f32 v[6:7], v[10:11], v[34:35]
	v_pk_add_f32 v[10:11], v[22:23], v[40:41]
	v_rcp_f32_e32 v22, v13
	v_xor_b32_e32 v33, 0x80000000, v33
	v_xor_b32_e32 v32, 0x80000000, v32
	v_xor_b32_e32 v35, 0x80000000, v35
	v_fma_f32 v23, -v13, v22, 1.0
	v_fmac_f32_e32 v22, v23, v22
	v_div_scale_f32 v23, vcc, 1.0, v12, 1.0
	v_mul_f32_e32 v25, v23, v22
	v_fma_f32 v31, -v13, v25, v23
	v_fmac_f32_e32 v25, v31, v22
	v_fma_f32 v13, -v13, v25, v23
	v_div_fmas_f32 v13, v13, v22, v25
	v_div_fixup_f32 v12, v13, v12, 1.0
	v_xor_b32_e32 v34, 0x80000000, v34
	v_lshl_add_u64 v[22:23], v[16:17], 0, v[36:37]
	v_pk_fma_f32 v[36:37], v[12:13], v[4:5], v[32:33] op_sel_hi:[0,1,1]
	v_xor_b32_e32 v33, 0x80000000, v39
	v_xor_b32_e32 v32, 0x80000000, v38
	v_pk_fma_f32 v[38:39], v[12:13], v[6:7], v[34:35] op_sel_hi:[0,1,1]
	v_xor_b32_e32 v35, 0x80000000, v41
	v_xor_b32_e32 v34, 0x80000000, v40
	v_pk_fma_f32 v[32:33], v[12:13], v[8:9], v[32:33] op_sel_hi:[0,1,1]
	v_pk_fma_f32 v[12:13], v[12:13], v[10:11], v[34:35] op_sel_hi:[0,1,1]
	v_cvt_pk_bf16_f32 v32, v32, v33
	v_cvt_pk_bf16_f32 v33, v36, v37
	v_cvt_pk_bf16_f32 v34, v12, v13
	v_cvt_pk_bf16_f32 v35, v38, v39
	v_cmp_ge_u32_e32 vcc, v21, v27
	global_store_dwordx4 v[22:23], v[32:35], off
	s_and_saveexec_b64 s[6:7], vcc
	s_cbranch_execz .LBB0_606
	v_sub_u32_e32 v12, v24, v27
	v_or_b32_e32 v12, 1, v12
	v_ashrrev_i32_e32 v13, 31, v12
	v_lshlrev_b64 v[12:13], 11, v[12:13]
	v_lshl_add_u64 v[12:13], v[14:15], 0, v[12:13]
	v_subrev_u32_e32 v22, s98, v12
	ds_read_b128 v[22:25], v22
	s_waitcnt lgkmcnt(0)
	v_lshlrev_b32_e32 v12, 16, v22
	v_and_b32_e32 v13, 0xffff0000, v22
	v_lshlrev_b32_e32 v21, 16, v23
	v_and_b32_e32 v22, 0xffff0000, v23
	v_lshlrev_b32_e32 v23, 16, v24
	v_and_b32_e32 v24, 0xffff0000, v24
	v_lshlrev_b32_e32 v31, 16, v25
	v_and_b32_e32 v25, 0xffff0000, v25
	v_sub_f32_e32 v5, v5, v22
	v_sub_f32_e32 v4, v4, v21
	v_sub_f32_e32 v9, v9, v13
	v_sub_f32_e32 v8, v8, v12
	v_sub_f32_e32 v7, v7, v25
	v_sub_f32_e32 v6, v6, v31
	v_sub_f32_e32 v11, v11, v24
	v_sub_f32_e32 v10, v10, v23
; __device__ __forceinline__ void p_pool(Frame& F) {
;     ...
;         for (int i = 0; i < 8; ++i) { const int t = t0 + i; f32x4 a, b; ld_bf16x8(ZP + (size_t)(r0 + i) * PD + 8 * cg, a, b); s0 += a; s1 += b;
;             const float inv = 1.0f / (float)((t + 1) < w ? (t + 1) : w);
;             st_bf16x8(PO + (size_t)(r0 + i) * PD + 8 * cg, s0 * inv - a, s1 * inv - b);
;             if (t - w + 1 >= 0) { f32x4 c, d; ld_bf16x8(ZP + (size_t)(r0 + i - w + 1) * PD + 8 * cg, c, d); s0 -= c; s1 -= d; } }
.LBB0_606:
	s_or_b64 exec, exec, s[6:7]
	v_or_b32_e32 v12, 5, v20
	v_ashrrev_i32_e32 v13, 31, v12
	v_lshlrev_b64 v[32:33], 11, v[12:13]
	v_lshl_add_u64 v[22:23], v[14:15], 0, v[32:33]
	v_subrev_u32_e32 v22, s98, v22
	ds_read_b128 v[22:25], v22
	v_or_b32_e32 v21, 6, v29
	v_min_u32_e32 v13, v21, v27
	v_cvt_f32_ubyte0_e32 v13, v13
	v_div_scale_f32 v31, s[6:7], v13, v13, 1.0
	v_rcp_f32_e32 v38, v31
	v_lshl_add_u64 v[32:33], v[16:17], 0, v[32:33]
	v_fma_f32 v39, -v31, v38, 1.0
	v_fmac_f32_e32 v38, v39, v38
	v_div_scale_f32 v39, vcc, 1.0, v13, 1.0
	v_mul_f32_e32 v40, v39, v38
	v_fma_f32 v41, -v31, v40, v39
	v_fmac_f32_e32 v40, v41, v38
	v_fma_f32 v31, -v31, v40, v39
	v_div_fmas_f32 v31, v31, v38, v40
	v_div_fixup_f32 v38, v31, v13, 1.0
	v_cmp_gt_i32_e32 vcc, v2, v28
	s_waitcnt lgkmcnt(0)
	v_lshlrev_b32_e32 v34, 16, v22
	v_and_b32_e32 v35, 0xffff0000, v22
	v_lshlrev_b32_e32 v22, 16, v23
	v_and_b32_e32 v23, 0xffff0000, v23
	v_lshlrev_b32_e32 v36, 16, v24
	v_and_b32_e32 v37, 0xffff0000, v24
	v_lshlrev_b32_e32 v24, 16, v25
	v_and_b32_e32 v25, 0xffff0000, v25
	v_pk_add_f32 v[4:5], v[4:5], v[22:23]
	v_pk_add_f32 v[6:7], v[6:7], v[24:25]
	v_xor_b32_e32 v23, 0x80000000, v23
	v_xor_b32_e32 v22, 0x80000000, v22
	v_xor_b32_e32 v25, 0x80000000, v25
	v_xor_b32_e32 v24, 0x80000000, v24
	v_pk_add_f32 v[8:9], v[8:9], v[34:35]
	v_pk_add_f32 v[10:11], v[10:11], v[36:37]
	v_pk_fma_f32 v[40:41], v[38:39], v[4:5], v[22:23] op_sel_hi:[0,1,1]
	v_xor_b32_e32 v23, 0x80000000, v35
	v_xor_b32_e32 v22, 0x80000000, v34
	v_pk_fma_f32 v[34:35], v[38:39], v[6:7], v[24:25] op_sel_hi:[0,1,1]
	v_xor_b32_e32 v25, 0x80000000, v37
	v_xor_b32_e32 v24, 0x80000000, v36
	v_pk_fma_f32 v[22:23], v[38:39], v[8:9], v[22:23] op_sel_hi:[0,1,1]
	v_pk_fma_f32 v[24:25], v[38:39], v[10:11], v[24:25] op_sel_hi:[0,1,1]
	v_cvt_pk_bf16_f32 v22, v22, v23
	v_cvt_pk_bf16_f32 v23, v40, v41
	v_cvt_pk_bf16_f32 v24, v24, v25
	v_cvt_pk_bf16_f32 v25, v34, v35
	global_store_dwordx4 v[32:33], v[22:25], off
	s_and_saveexec_b64 s[6:7], vcc
	s_cbranch_execz .LBB0_608
	v_sub_u32_e32 v12, v12, v27
	v_ashrrev_i32_e32 v13, 31, v12
	v_lshlrev_b64 v[12:13], 11, v[12:13]
	v_lshl_add_u64 v[12:13], v[14:15], 0, v[12:13]
	v_subrev_u32_e32 v22, s98, v12
	ds_read_b128 v[22:25], v22 offset:2048
	s_waitcnt lgkmcnt(0)
	v_lshlrev_b32_e32 v2, 16, v22
	v_and_b32_e32 v12, 0xffff0000, v22
	v_lshlrev_b32_e32 v13, 16, v23
	v_and_b32_e32 v22, 0xffff0000, v23
	v_lshlrev_b32_e32 v23, 16, v24
	v_and_b32_e32 v24, 0xffff0000, v24
	v_lshlrev_b32_e32 v31, 16, v25
	v_and_b32_e32 v25, 0xffff0000, v25
	v_sub_f32_e32 v5, v5, v22
	v_sub_f32_e32 v4, v4, v13
	v_sub_f32_e32 v9, v9, v12
	v_sub_f32_e32 v8, v8, v2
	v_sub_f32_e32 v7, v7, v25
	v_sub_f32_e32 v6, v6, v31
	v_sub_f32_e32 v11, v11, v24
	v_sub_f32_e32 v10, v10, v23
.LBB0_608:
	s_or_b64 exec, exec, s[6:7]
	v_or_b32_e32 v12, 6, v20
	v_ashrrev_i32_e32 v13, 31, v12
	v_lshlrev_b64 v[32:33], 11, v[12:13]
	v_lshl_add_u64 v[22:23], v[14:15], 0, v[32:33]
	v_subrev_u32_e32 v22, s98, v22
	ds_read_b128 v[22:25], v22
	v_or_b32_e32 v2, 7, v29
	v_min_u32_e32 v2, v2, v27
	v_cvt_f32_ubyte0_e32 v2, v2
	v_div_scale_f32 v13, s[6:7], v2, v2, 1.0
	v_rcp_f32_e32 v20, v13
	v_lshl_add_u64 v[32:33], v[16:17], 0, v[32:33]
	v_fma_f32 v31, -v13, v20, 1.0
	v_fmac_f32_e32 v20, v31, v20
	v_div_scale_f32 v31, vcc, 1.0, v2, 1.0
	v_mul_f32_e32 v38, v31, v20
	v_fma_f32 v39, -v13, v38, v31
	v_fmac_f32_e32 v38, v39, v20
	v_fma_f32 v13, -v13, v38, v31
	v_div_fmas_f32 v13, v13, v20, v38
	v_div_fixup_f32 v2, v13, v2, 1.0
	v_cmp_ge_u32_e32 vcc, v21, v27
	s_waitcnt lgkmcnt(0)
	v_lshlrev_b32_e32 v34, 16, v22
	v_and_b32_e32 v35, 0xffff0000, v22
	v_lshlrev_b32_e32 v22, 16, v23
	v_and_b32_e32 v23, 0xffff0000, v23
	v_lshlrev_b32_e32 v36, 16, v24
	v_and_b32_e32 v37, 0xffff0000, v24
	v_lshlrev_b32_e32 v24, 16, v25
	v_and_b32_e32 v25, 0xffff0000, v25
	v_pk_add_f32 v[4:5], v[4:5], v[22:23]
	v_pk_add_f32 v[6:7], v[6:7], v[24:25]
	v_xor_b32_e32 v23, 0x80000000, v23
	v_xor_b32_e32 v22, 0x80000000, v22
	v_xor_b32_e32 v25, 0x80000000, v25
	v_xor_b32_e32 v24, 0x80000000, v24
	v_pk_add_f32 v[8:9], v[8:9], v[34:35]
	v_pk_add_f32 v[10:11], v[10:11], v[36:37]
	v_pk_fma_f32 v[38:39], v[2:3], v[4:5], v[22:23] op_sel_hi:[0,1,1]
	v_xor_b32_e32 v23, 0x80000000, v35
	v_xor_b32_e32 v22, 0x80000000, v34
	v_pk_fma_f32 v[34:35], v[2:3], v[6:7], v[24:25] op_sel_hi:[0,1,1]
	v_xor_b32_e32 v25, 0x80000000, v37
	v_xor_b32_e32 v24, 0x80000000, v36
	v_pk_fma_f32 v[22:23], v[2:3], v[8:9], v[22:23] op_sel_hi:[0,1,1]
	v_pk_fma_f32 v[24:25], v[2:3], v[10:11], v[24:25] op_sel_hi:[0,1,1]
	v_cvt_pk_bf16_f32 v22, v22, v23
	v_cvt_pk_bf16_f32 v23, v38, v39
	v_cvt_pk_bf16_f32 v24, v24, v25
	v_cvt_pk_bf16_f32 v25, v34, v35
	global_store_dwordx4 v[32:33], v[22:25], off
	s_and_saveexec_b64 s[6:7], vcc
	s_cbranch_execz .LBB0_591
	v_sub_u32_e32 v2, v12, v27
	v_or_b32_e32 v12, 1, v2
	v_ashrrev_i32_e32 v13, 31, v12
	v_lshlrev_b64 v[12:13], 11, v[12:13]
	v_lshl_add_u64 v[12:13], v[14:15], 0, v[12:13]
	v_subrev_u32_e32 v20, s98, v12
	ds_read_b128 v[20:23], v20
	s_waitcnt lgkmcnt(0)
	v_lshlrev_b32_e32 v2, 16, v20
	v_and_b32_e32 v12, 0xffff0000, v20
	v_lshlrev_b32_e32 v13, 16, v21
	v_and_b32_e32 v20, 0xffff0000, v21
	v_lshlrev_b32_e32 v21, 16, v22
	v_and_b32_e32 v22, 0xffff0000, v22
	v_lshlrev_b32_e32 v24, 16, v23
	v_and_b32_e32 v23, 0xffff0000, v23
	v_sub_f32_e32 v5, v5, v20
	v_sub_f32_e32 v4, v4, v13
	v_sub_f32_e32 v9, v9, v12
	v_sub_f32_e32 v8, v8, v2
	v_sub_f32_e32 v7, v7, v23
	v_sub_f32_e32 v6, v6, v24
	v_sub_f32_e32 v11, v11, v22
	v_sub_f32_e32 v10, v10, v21
	s_branch .LBB0_591
